# FFN-up K-loop: the compiler's per-phase s_setprio flips removed
# speedup vs baseline: 1.0025x; 1.0025x over previous
.LBB0_944:
	s_add_u32 s2, s66, 0xfffc0080
	s_addc_u32 s14, s67, -1
	s_add_i32 s15, 0, 0x10000
	s_cmp_eq_u32 s42, 12
	s_cselect_b32 s27, s18, s14
	s_cselect_b32 s26, s19, s2
	s_cselect_b32 s25, s8, s68
	s_cselect_b32 s24, s57, s61
	s_add_i32 s2, 0, 0x14000
	v_add_u32_e32 v142, s15, v187
	v_add_u32_e32 v170, s2, v187
	ds_read_b128 v[130:133], v142
	ds_read_b128 v[134:137], v142 offset:1024
	ds_read_b128 v[138:141], v142 offset:2048
	ds_read_b128 v[142:145], v142 offset:3072
	ds_read_b128 v[146:149], v170
	ds_read_b128 v[150:153], v170 offset:1024
	ds_read_b128 v[166:169], v170 offset:2048
	ds_read_b128 v[170:173], v170 offset:3072
	v_lshl_add_u64 v[182:183], s[66:67], 0, v[164:165]
	s_add_i32 m0, s47, 0xc000
	ds_read_b128 v[174:177], v191
	ds_read_b128 v[178:181], v191 offset:1024
	ds_read_b128 v[200:203], v191 offset:2048
	ds_read_b128 v[204:207], v191 offset:3072
	ds_read_b128 v[208:211], v191 offset:4096
	ds_read_b128 v[212:215], v191 offset:5120
	ds_read_b128 v[216:219], v191 offset:6144
	ds_read_b128 v[220:223], v191 offset:7168
	global_load_lds_dwordx4 v[182:183], off
	v_lshl_add_u64 v[182:183], s[66:67], 0, v[162:163]
	s_add_i32 m0, s47, 0xe000
	s_nop 0
	global_load_lds_dwordx4 v[182:183], off
	s_waitcnt vmcnt(8)
	s_waitcnt lgkmcnt(0)
	s_barrier
	s_waitcnt lgkmcnt(0)
	v_mfma_f32_16x16x32_bf16 v[126:129], v[130:133], v[174:177], v[126:129]
	v_mfma_f32_16x16x32_bf16 v[118:121], v[138:141], v[174:177], v[118:121]
	v_mfma_f32_16x16x32_bf16 v[110:113], v[130:133], v[200:203], v[110:113]
	v_mfma_f32_16x16x32_bf16 v[102:105], v[138:141], v[200:203], v[102:105]
	v_mfma_f32_16x16x32_bf16 v[92:95], v[130:133], v[208:211], v[92:95]
	v_mfma_f32_16x16x32_bf16 v[84:87], v[138:141], v[208:211], v[84:87]
	v_mfma_f32_16x16x32_bf16 v[76:79], v[130:133], v[216:219], v[76:79]
	v_mfma_f32_16x16x32_bf16 v[68:71], v[138:141], v[216:219], v[68:71]
	v_mfma_f32_16x16x32_bf16 v[126:129], v[134:137], v[178:181], v[126:129]
	v_mfma_f32_16x16x32_bf16 v[118:121], v[142:145], v[178:181], v[118:121]
	v_mfma_f32_16x16x32_bf16 v[110:113], v[134:137], v[204:207], v[110:113]
	v_mfma_f32_16x16x32_bf16 v[102:105], v[142:145], v[204:207], v[102:105]
	v_mfma_f32_16x16x32_bf16 v[92:95], v[134:137], v[212:215], v[92:95]
	v_mfma_f32_16x16x32_bf16 v[84:87], v[142:145], v[212:215], v[84:87]
	v_mfma_f32_16x16x32_bf16 v[76:79], v[134:137], v[220:223], v[76:79]
	v_mfma_f32_16x16x32_bf16 v[68:71], v[142:145], v[220:223], v[68:71]
	v_mfma_f32_16x16x32_bf16 v[122:125], v[146:149], v[174:177], v[122:125]
	v_mfma_f32_16x16x32_bf16 v[114:117], v[166:169], v[174:177], v[114:117]
	v_mfma_f32_16x16x32_bf16 v[106:109], v[146:149], v[200:203], v[106:109]
	v_mfma_f32_16x16x32_bf16 v[98:101], v[166:169], v[200:203], v[98:101]
	v_mfma_f32_16x16x32_bf16 v[88:91], v[146:149], v[208:211], v[88:91]
	v_mfma_f32_16x16x32_bf16 v[80:83], v[166:169], v[208:211], v[80:83]
	v_mfma_f32_16x16x32_bf16 v[72:75], v[146:149], v[216:219], v[72:75]
	v_mfma_f32_16x16x32_bf16 v[64:67], v[166:169], v[216:219], v[64:67]
	v_mfma_f32_16x16x32_bf16 v[122:125], v[150:153], v[178:181], v[122:125]
	v_mfma_f32_16x16x32_bf16 v[114:117], v[170:173], v[178:181], v[114:117]
	v_mfma_f32_16x16x32_bf16 v[106:109], v[150:153], v[204:207], v[106:109]
	v_mfma_f32_16x16x32_bf16 v[98:101], v[170:173], v[204:207], v[98:101]
	v_mfma_f32_16x16x32_bf16 v[88:91], v[150:153], v[212:215], v[88:91]
	v_mfma_f32_16x16x32_bf16 v[80:83], v[170:173], v[212:215], v[80:83]
	v_mfma_f32_16x16x32_bf16 v[72:75], v[150:153], v[220:223], v[72:75]
	v_mfma_f32_16x16x32_bf16 v[64:67], v[170:173], v[220:223], v[64:67]
	s_barrier
	s_add_i32 s14, s15, s39
	v_lshl_add_u64 v[182:183], s[24:25], 0, v[96:97]
	s_mov_b32 m0, s14
	ds_read_b128 v[174:177], v191 offset:16384
	ds_read_b128 v[178:181], v191 offset:17408
	ds_read_b128 v[200:203], v191 offset:18432
	ds_read_b128 v[204:207], v191 offset:19456
	ds_read_b128 v[208:211], v191 offset:20480
	ds_read_b128 v[212:215], v191 offset:21504
	ds_read_b128 v[216:219], v191 offset:22528
	ds_read_b128 v[220:223], v191 offset:23552
	global_load_lds_dwordx4 v[182:183], off
	s_add_i32 m0, s14, 0x2000
	s_add_u32 s14, s24, 0x40000
	v_lshl_add_u64 v[188:189], s[24:25], 0, v[154:155]
	s_addc_u32 s15, s25, 0
	s_add_i32 s2, s2, s39
	global_load_lds_dwordx4 v[188:189], off
	v_lshl_add_u64 v[192:193], s[14:15], 0, v[96:97]
	s_mov_b32 m0, s2
	v_lshl_add_u64 v[224:225], s[26:27], 0, v[156:157]
	global_load_lds_dwordx4 v[192:193], off
	v_lshl_add_u64 v[192:193], s[14:15], 0, v[154:155]
	s_add_i32 m0, s2, 0x2000
	s_nop 0
	global_load_lds_dwordx4 v[192:193], off
	v_lshl_add_u64 v[192:193], s[26:27], 0, v[158:159]
	s_mov_b32 m0, s47
	s_nop 0
	global_load_lds_dwordx4 v[192:193], off
	s_mov_b32 m0, s70
	s_nop 0
	global_load_lds_dwordx4 v[224:225], off
	s_waitcnt vmcnt(8)
	s_waitcnt lgkmcnt(0)
	s_barrier
	s_waitcnt lgkmcnt(0)
	v_mfma_f32_16x16x32_bf16 v[60:63], v[130:133], v[174:177], v[60:63]
	v_mfma_f32_16x16x32_bf16 v[52:55], v[138:141], v[174:177], v[52:55]
	v_mfma_f32_16x16x32_bf16 v[44:47], v[130:133], v[200:203], v[44:47]
	v_mfma_f32_16x16x32_bf16 v[36:39], v[138:141], v[200:203], v[36:39]
	v_mfma_f32_16x16x32_bf16 v[28:31], v[130:133], v[208:211], v[28:31]
	v_mfma_f32_16x16x32_bf16 v[20:23], v[138:141], v[208:211], v[20:23]
	v_mfma_f32_16x16x32_bf16 v[12:15], v[130:133], v[216:219], v[12:15]
	v_mfma_f32_16x16x32_bf16 v[4:7], v[138:141], v[216:219], v[4:7]
	v_mfma_f32_16x16x32_bf16 v[60:63], v[134:137], v[178:181], v[60:63]
	v_mfma_f32_16x16x32_bf16 v[52:55], v[142:145], v[178:181], v[52:55]
	v_mfma_f32_16x16x32_bf16 v[44:47], v[134:137], v[204:207], v[44:47]
	v_mfma_f32_16x16x32_bf16 v[36:39], v[142:145], v[204:207], v[36:39]
	v_mfma_f32_16x16x32_bf16 v[28:31], v[134:137], v[212:215], v[28:31]
	v_mfma_f32_16x16x32_bf16 v[20:23], v[142:145], v[212:215], v[20:23]
	v_mfma_f32_16x16x32_bf16 v[12:15], v[134:137], v[220:223], v[12:15]
	v_mfma_f32_16x16x32_bf16 v[4:7], v[142:145], v[220:223], v[4:7]
	v_mfma_f32_16x16x32_bf16 v[56:59], v[146:149], v[174:177], v[56:59]
	v_mfma_f32_16x16x32_bf16 v[48:51], v[166:169], v[174:177], v[48:51]
	v_mfma_f32_16x16x32_bf16 v[40:43], v[146:149], v[200:203], v[40:43]
	v_mfma_f32_16x16x32_bf16 v[32:35], v[166:169], v[200:203], v[32:35]
	v_mfma_f32_16x16x32_bf16 v[24:27], v[146:149], v[208:211], v[24:27]
	v_mfma_f32_16x16x32_bf16 v[16:19], v[166:169], v[208:211], v[16:19]
	v_mfma_f32_16x16x32_bf16 v[8:11], v[146:149], v[216:219], v[8:11]
	v_mfma_f32_16x16x32_bf16 v[0:3], v[166:169], v[216:219], v[0:3]
	v_mfma_f32_16x16x32_bf16 v[56:59], v[150:153], v[178:181], v[56:59]
	v_mfma_f32_16x16x32_bf16 v[48:51], v[170:173], v[178:181], v[48:51]
	v_mfma_f32_16x16x32_bf16 v[40:43], v[150:153], v[204:207], v[40:43]
	v_mfma_f32_16x16x32_bf16 v[32:35], v[170:173], v[204:207], v[32:35]
	v_mfma_f32_16x16x32_bf16 v[24:27], v[150:153], v[212:215], v[24:27]
	v_mfma_f32_16x16x32_bf16 v[16:19], v[170:173], v[212:215], v[16:19]
	v_mfma_f32_16x16x32_bf16 v[8:11], v[150:153], v[220:223], v[8:11]
	v_mfma_f32_16x16x32_bf16 v[0:3], v[170:173], v[220:223], v[0:3]
	s_barrier
	s_add_i32 s2, 0, 0x18000
	s_add_i32 s20, 0, 0x1c000
	v_add_u32_e32 v142, s2, v187
	v_add_u32_e32 v170, s20, v187
	ds_read_b128 v[130:133], v142
	ds_read_b128 v[134:137], v142 offset:1024
	ds_read_b128 v[138:141], v142 offset:2048
	ds_read_b128 v[142:145], v142 offset:3072
	ds_read_b128 v[146:149], v170
	ds_read_b128 v[150:153], v170 offset:1024
	ds_read_b128 v[166:169], v170 offset:2048
	ds_read_b128 v[170:173], v170 offset:3072
	s_add_u32 s14, s26, 0x40000
	s_addc_u32 s15, s27, 0
	s_mov_b32 m0, s71
	v_lshl_add_u64 v[226:227], s[14:15], 0, v[158:159]
	ds_read_b128 v[174:177], v191 offset:32768
	ds_read_b128 v[178:181], v191 offset:33792
	ds_read_b128 v[200:203], v191 offset:34816
	ds_read_b128 v[204:207], v191 offset:35840
	ds_read_b128 v[208:211], v191 offset:36864
	ds_read_b128 v[212:215], v191 offset:37888
	ds_read_b128 v[216:219], v191 offset:38912
	ds_read_b128 v[220:223], v191 offset:39936
	global_load_lds_dwordx4 v[226:227], off
	v_lshl_add_u64 v[226:227], s[14:15], 0, v[156:157]
	s_mov_b32 m0, s72
	s_nop 0
	global_load_lds_dwordx4 v[226:227], off
	s_waitcnt vmcnt(8)
	s_waitcnt lgkmcnt(0)
	s_barrier
	s_waitcnt lgkmcnt(0)
	v_mfma_f32_16x16x32_bf16 v[126:129], v[130:133], v[174:177], v[126:129]
	v_mfma_f32_16x16x32_bf16 v[118:121], v[138:141], v[174:177], v[118:121]
	v_mfma_f32_16x16x32_bf16 v[110:113], v[130:133], v[200:203], v[110:113]
	v_mfma_f32_16x16x32_bf16 v[102:105], v[138:141], v[200:203], v[102:105]
	v_mfma_f32_16x16x32_bf16 v[92:95], v[130:133], v[208:211], v[92:95]
	v_mfma_f32_16x16x32_bf16 v[84:87], v[138:141], v[208:211], v[84:87]
	v_mfma_f32_16x16x32_bf16 v[76:79], v[130:133], v[216:219], v[76:79]
	v_mfma_f32_16x16x32_bf16 v[68:71], v[138:141], v[216:219], v[68:71]
	v_mfma_f32_16x16x32_bf16 v[126:129], v[134:137], v[178:181], v[126:129]
	v_mfma_f32_16x16x32_bf16 v[118:121], v[142:145], v[178:181], v[118:121]
	v_mfma_f32_16x16x32_bf16 v[110:113], v[134:137], v[204:207], v[110:113]
	v_mfma_f32_16x16x32_bf16 v[102:105], v[142:145], v[204:207], v[102:105]
	v_mfma_f32_16x16x32_bf16 v[92:95], v[134:137], v[212:215], v[92:95]
	v_mfma_f32_16x16x32_bf16 v[84:87], v[142:145], v[212:215], v[84:87]
	v_mfma_f32_16x16x32_bf16 v[76:79], v[134:137], v[220:223], v[76:79]
	v_mfma_f32_16x16x32_bf16 v[68:71], v[142:145], v[220:223], v[68:71]
	v_mfma_f32_16x16x32_bf16 v[122:125], v[146:149], v[174:177], v[122:125]
	v_mfma_f32_16x16x32_bf16 v[114:117], v[166:169], v[174:177], v[114:117]
	v_mfma_f32_16x16x32_bf16 v[106:109], v[146:149], v[200:203], v[106:109]
	v_mfma_f32_16x16x32_bf16 v[98:101], v[166:169], v[200:203], v[98:101]
	v_mfma_f32_16x16x32_bf16 v[88:91], v[146:149], v[208:211], v[88:91]
	v_mfma_f32_16x16x32_bf16 v[80:83], v[166:169], v[208:211], v[80:83]
	v_mfma_f32_16x16x32_bf16 v[72:75], v[146:149], v[216:219], v[72:75]
	v_mfma_f32_16x16x32_bf16 v[64:67], v[166:169], v[216:219], v[64:67]
	v_mfma_f32_16x16x32_bf16 v[122:125], v[150:153], v[178:181], v[122:125]
	v_mfma_f32_16x16x32_bf16 v[114:117], v[170:173], v[178:181], v[114:117]
	v_mfma_f32_16x16x32_bf16 v[106:109], v[150:153], v[204:207], v[106:109]
	v_mfma_f32_16x16x32_bf16 v[98:101], v[170:173], v[204:207], v[98:101]
	v_mfma_f32_16x16x32_bf16 v[88:91], v[150:153], v[212:215], v[88:91]
	v_mfma_f32_16x16x32_bf16 v[80:83], v[170:173], v[212:215], v[80:83]
	v_mfma_f32_16x16x32_bf16 v[72:75], v[150:153], v[220:223], v[72:75]
	v_mfma_f32_16x16x32_bf16 v[64:67], v[170:173], v[220:223], v[64:67]
	s_barrier
	s_add_i32 s2, s2, s39
	v_lshl_add_u64 v[182:183], v[182:183], 0, s[22:23]
	s_mov_b32 m0, s2
	ds_read_b128 v[174:177], v191 offset:49152
	ds_read_b128 v[178:181], v191 offset:50176
	ds_read_b128 v[200:203], v191 offset:51200
	ds_read_b128 v[204:207], v191 offset:52224
	ds_read_b128 v[208:211], v191 offset:53248
	ds_read_b128 v[212:215], v191 offset:54272
	ds_read_b128 v[216:219], v191 offset:55296
	ds_read_b128 v[220:223], v191 offset:56320
	global_load_lds_dwordx4 v[182:183], off
	s_add_i32 m0, s2, 0x2000
	s_add_u32 s14, s24, 0x40080
	v_lshl_add_u64 v[182:183], v[188:189], 0, s[22:23]
	s_addc_u32 s15, s25, 0
	s_add_i32 s2, s20, s39
	global_load_lds_dwordx4 v[182:183], off
	v_lshl_add_u64 v[182:183], s[14:15], 0, v[96:97]
	s_mov_b32 m0, s2
	s_nop 0
	global_load_lds_dwordx4 v[182:183], off
	v_lshl_add_u64 v[182:183], s[14:15], 0, v[154:155]
	s_add_i32 m0, s2, 0x2000
	s_nop 0
	global_load_lds_dwordx4 v[182:183], off
	v_lshl_add_u64 v[182:183], v[192:193], 0, s[22:23]
	s_mov_b32 m0, s73
	s_nop 0
	global_load_lds_dwordx4 v[182:183], off
	v_lshl_add_u64 v[182:183], v[224:225], 0, s[22:23]
	s_mov_b32 m0, s74
	s_nop 0
	global_load_lds_dwordx4 v[182:183], off
	s_waitcnt vmcnt(8)
	s_waitcnt lgkmcnt(0)
	s_barrier
	s_waitcnt lgkmcnt(0)
	v_mfma_f32_16x16x32_bf16 v[60:63], v[130:133], v[174:177], v[60:63]
	v_mfma_f32_16x16x32_bf16 v[52:55], v[138:141], v[174:177], v[52:55]
	v_mfma_f32_16x16x32_bf16 v[44:47], v[130:133], v[200:203], v[44:47]
	v_mfma_f32_16x16x32_bf16 v[36:39], v[138:141], v[200:203], v[36:39]
	v_mfma_f32_16x16x32_bf16 v[28:31], v[130:133], v[208:211], v[28:31]
	v_mfma_f32_16x16x32_bf16 v[20:23], v[138:141], v[208:211], v[20:23]
	v_mfma_f32_16x16x32_bf16 v[12:15], v[130:133], v[216:219], v[12:15]
	v_mfma_f32_16x16x32_bf16 v[4:7], v[138:141], v[216:219], v[4:7]
	v_mfma_f32_16x16x32_bf16 v[60:63], v[134:137], v[178:181], v[60:63]
	v_mfma_f32_16x16x32_bf16 v[52:55], v[142:145], v[178:181], v[52:55]
	v_mfma_f32_16x16x32_bf16 v[44:47], v[134:137], v[204:207], v[44:47]
	v_mfma_f32_16x16x32_bf16 v[36:39], v[142:145], v[204:207], v[36:39]
	v_mfma_f32_16x16x32_bf16 v[28:31], v[134:137], v[212:215], v[28:31]
	v_mfma_f32_16x16x32_bf16 v[20:23], v[142:145], v[212:215], v[20:23]
	v_mfma_f32_16x16x32_bf16 v[12:15], v[134:137], v[220:223], v[12:15]
	v_mfma_f32_16x16x32_bf16 v[4:7], v[142:145], v[220:223], v[4:7]
	v_mfma_f32_16x16x32_bf16 v[56:59], v[146:149], v[174:177], v[56:59]
	v_mfma_f32_16x16x32_bf16 v[48:51], v[166:169], v[174:177], v[48:51]
	v_mfma_f32_16x16x32_bf16 v[40:43], v[146:149], v[200:203], v[40:43]
	v_mfma_f32_16x16x32_bf16 v[32:35], v[166:169], v[200:203], v[32:35]
	v_mfma_f32_16x16x32_bf16 v[24:27], v[146:149], v[208:211], v[24:27]
	v_mfma_f32_16x16x32_bf16 v[16:19], v[166:169], v[208:211], v[16:19]
	v_mfma_f32_16x16x32_bf16 v[8:11], v[146:149], v[216:219], v[8:11]
	v_mfma_f32_16x16x32_bf16 v[0:3], v[166:169], v[216:219], v[0:3]
	v_mfma_f32_16x16x32_bf16 v[56:59], v[150:153], v[178:181], v[56:59]
	v_mfma_f32_16x16x32_bf16 v[48:51], v[170:173], v[178:181], v[48:51]
	v_mfma_f32_16x16x32_bf16 v[40:43], v[150:153], v[204:207], v[40:43]
	v_mfma_f32_16x16x32_bf16 v[32:35], v[170:173], v[204:207], v[32:35]
	v_mfma_f32_16x16x32_bf16 v[24:27], v[150:153], v[212:215], v[24:27]
	v_mfma_f32_16x16x32_bf16 v[16:19], v[170:173], v[212:215], v[16:19]
	v_mfma_f32_16x16x32_bf16 v[8:11], v[150:153], v[220:223], v[8:11]
	v_mfma_f32_16x16x32_bf16 v[0:3], v[170:173], v[220:223], v[0:3]
	s_barrier
	s_add_i32 s42, s42, 2
	s_add_u32 s61, s61, 0x100
	s_addc_u32 s68, s68, 0
	s_add_u32 s66, s66, 0x100
	s_addc_u32 s67, s67, 0
	s_cmp_gt_u32 s42, 13
	s_cbranch_scc0 .LBB0_944
	v_lshl_add_u32 v180, s4, 8, v185
	v_lshl_add_u32 v199, s60, 8, v185
	v_mov_b32_e32 v251, 0
	v_lshlrev_b32_e32 v250, 6, v199
	v_lshl_add_u64 v[194:195], v[160:161], 0, v[250:251]
	global_load_dwordx4 v[200:203], v[194:195], off
	v_add_u32_e32 v250, 0x10, v199
	v_lshlrev_b32_e32 v250, 6, v250
	v_lshl_add_u64 v[194:195], v[160:161], 0, v[250:251]
	global_load_dwordx4 v[204:207], v[194:195], off
	v_add_u32_e32 v250, 0x20, v199
	v_lshlrev_b32_e32 v250, 6, v250
	v_lshl_add_u64 v[194:195], v[160:161], 0, v[250:251]
	global_load_dwordx4 v[150:153], v[194:195], off
	v_add_u32_e32 v250, 0x30, v199
	v_lshlrev_b32_e32 v250, 6, v250
	v_lshl_add_u64 v[194:195], v[160:161], 0, v[250:251]
	global_load_dwordx4 v[146:149], v[194:195], off
	v_add_u32_e32 v250, 0x80, v199
	v_lshlrev_b32_e32 v250, 6, v250
	v_lshl_add_u64 v[194:195], v[160:161], 0, v[250:251]
	global_load_dwordx4 v[142:145], v[194:195], off
	v_add_u32_e32 v250, 0x90, v199
	v_lshlrev_b32_e32 v250, 6, v250
	v_lshl_add_u64 v[194:195], v[160:161], 0, v[250:251]
	global_load_dwordx4 v[138:141], v[194:195], off
	v_add_u32_e32 v250, 0xa0, v199
	v_lshlrev_b32_e32 v250, 6, v250
	v_lshl_add_u64 v[194:195], v[160:161], 0, v[250:251]
	global_load_dwordx4 v[134:137], v[194:195], off
	v_add_u32_e32 v250, 0xb0, v199
	v_lshlrev_b32_e32 v250, 6, v250
	v_lshl_add_u64 v[194:195], v[160:161], 0, v[250:251]
	global_load_dwordx4 v[130:133], v[194:195], off
	v_or_b32_e32 v178, 16, v180
	v_or_b32_e32 v176, 32, v180
	v_or_b32_e32 v174, 48, v180
	v_add_u32_e32 v172, 0x80, v180
	v_add_u32_e32 v170, 0x90, v180
	v_add_u32_e32 v168, 0xa0, v180
	v_add_u32_e32 v166, 0xb0, v180
	s_and_b64 vcc, exec, s[58:59]
	s_cbranch_vccz .LBB0_947
	s_barrier
